# generated position-DFT matrix written with non-temporal stores (read nine phases later; keeps the mixer GEMM operands in L2)
# speedup vs baseline: 1.0442x; 1.0083x over previous
; __device__ __forceinline__ unsigned cvt_pk_bf16(float lo, float hi) { unsigned r; asm volatile("v_cvt_pk_bf16_f32 %0, %1, %2" : "=v"(r) : "v"(lo), "v"(hi)); return r; }
; #define ST16(grp, p, v) do { if ((NTG >> (grp)) & 1) NT16(p, v); else PL16(p, v); } while (0)
; __device__ __forceinline__ void gen_dftl(unsigned char* ws, LAS unsigned char* lds, int first) {
;     ...
;     for (int k = bi * 8 + wave; k < 2048; k += nb * 8) {
;         float cj[8], sj[8];
; #pragma unroll
;         for (int j = 0; j < 8; ++j) { const int idx = (k * j) & 4095; cj[j] = lut[idx] * 0.015625f; sj[j] = lut[(idx - 1024) & 4095] * 0.015625f; }
; #pragma unroll
;         for (int i = 0; i < 8; ++i) { const int n0 = 8 * (lane + 64 * i), idx0 = (k * n0) & 4095; const float c0 = lut[idx0], s0 = lut[(idx0 - 1024) & 4095]; float vc[8], vs[8];
; #pragma unroll
;             for (int j = 0; j < 8; ++j) { vc[j] = c0 * cj[j] - s0 * sj[j]; vs[j] = s0 * cj[j] + c0 * sj[j]; }
;             u32x4 o; o.x = cvt_pk_bf16(vc[0], vc[1]); o.y = cvt_pk_bf16(vc[2], vc[3]); o.z = cvt_pk_bf16(vc[4], vc[5]); o.w = cvt_pk_bf16(vc[6], vc[7]);
;             ST16(6, DL + (size_t)k * 8192 + n0, o);
;             o.x = cvt_pk_bf16(vs[0], vs[1]); o.y = cvt_pk_bf16(vs[2], vs[3]); o.z = cvt_pk_bf16(vs[4], vs[5]); o.w = cvt_pk_bf16(vs[6], vs[7]);
;             ST16(6, DL + (size_t)k * 8192 + 4096 + n0, o); }
;     }
.LBB0_424:
	v_add_u32_e32 v13, 0xc00, v0
	v_add_u32_e32 v14, 0xfffff400, v26
	v_add_u32_e32 v16, 0xfffff400, v27
	v_add_u32_e32 v18, 0xfffff400, v28
	v_add_u32_e32 v20, 0xfffff400, v29
	v_add_u32_e32 v49, v32, v1
	v_add_u32_e32 v50, v32, v46
	v_add_u32_e32 v51, v32, v44
	v_add_u32_e32 v52, v32, v42
	v_add_u32_e32 v53, v32, v40
	v_add_u32_e32 v54, v32, v38
	v_add_u32_e32 v55, v32, v36
	v_add_u32_e32 v56, v32, v33
	v_and_b32_e32 v12, 0xfff, v0
	v_and_b32_e32 v15, 0xffe, v26
	v_and_b32_e32 v17, 0xfff, v27
	v_add_u32_e32 v22, 0xfffff400, v30
	v_add_u32_e32 v24, 0xfffff400, v31
	v_and_b32_e32 v13, 0xfff, v13
	v_and_b32_e32 v14, 0xffe, v14
	v_and_b32_e32 v16, 0xfff, v16
	v_and_b32_e32 v18, 0xffc, v18
	v_and_b32_e32 v20, 0xfff, v20
	v_and_b32_e32 v57, 0xff8, v49
	v_add_u32_e32 v49, 0xc00, v49
	v_add_u32_e32 v58, 0xfff80000, v50
	v_add_u32_e32 v59, 0xfff00000, v51
	v_add_u32_e32 v60, 0xffe80000, v52
	v_add_u32_e32 v52, 0xffe80c00, v52
	v_add_u32_e32 v61, 0xffe00000, v53
	v_add_u32_e32 v53, 0xffe00c00, v53
	v_add_u32_e32 v62, 0xffd80000, v54
	v_add_u32_e32 v54, 0xffd80c00, v54
	v_add_u32_e32 v63, 0xffd00000, v55
	v_add_u32_e32 v55, 0xffd00c00, v55
	v_add_u32_e32 v64, 0xffc80000, v56
	v_add_u32_e32 v56, 0xffc80c00, v56
	ds_read2st64_b32 v[8:9], v48 offset1:48
	v_and_b32_e32 v19, 0xffc, v28
	v_and_b32_e32 v21, 0xfff, v29
	v_and_b32_e32 v23, 0xffe, v30
	v_and_b32_e32 v25, 0xfff, v31
	v_lshl_add_u32 v12, v12, 2, 0
	v_lshl_add_u32 v15, v15, 2, 0
	v_lshl_add_u32 v17, v17, 2, 0
	v_and_b32_e32 v22, 0xffe, v22
	v_and_b32_e32 v24, 0xfff, v24
	v_add_u32_e32 v50, 0xfff80c00, v50
	v_add_u32_e32 v51, 0xfff00c00, v51
	v_lshl_add_u32 v13, v13, 2, 0
	v_lshl_add_u32 v14, v14, 2, 0
	v_lshl_add_u32 v16, v16, 2, 0
	v_lshl_add_u32 v18, v18, 2, 0
	v_lshl_add_u32 v20, v20, 2, 0
	v_lshl_add_u32 v57, v57, 2, 0
	v_and_b32_e32 v49, 0xff8, v49
	v_and_b32_e32 v58, 0xff8, v58
	v_and_b32_e32 v59, 0xff8, v59
	v_and_b32_e32 v52, 0xff8, v52
	v_and_b32_e32 v53, 0xff8, v53
	v_and_b32_e32 v54, 0xff8, v54
	v_and_b32_e32 v55, 0xff8, v55
	v_and_b32_e32 v56, 0xff8, v56
	v_lshl_add_u32 v19, v19, 2, 0
	v_lshl_add_u32 v21, v21, 2, 0
	v_lshl_add_u32 v23, v23, 2, 0
	v_lshl_add_u32 v25, v25, 2, 0
	v_lshl_add_u32 v22, v22, 2, 0
	v_lshl_add_u32 v24, v24, 2, 0
	v_and_b32_e32 v65, 0xff8, v50
	v_and_b32_e32 v66, 0xff8, v51
	ds_read_b32 v12, v12
	ds_read_b32 v13, v13
	ds_read_b32 v14, v14
	ds_read_b32 v15, v15
	ds_read_b32 v16, v16
	ds_read_b32 v17, v17
	ds_read_b32 v50, v18
	ds_read_b32 v51, v19
	v_lshl_add_u32 v18, v49, 2, 0
	v_lshl_add_u32 v49, v58, 2, 0
	v_lshl_add_u32 v69, v59, 2, 0
	v_lshl_add_u32 v72, v52, 2, 0
	v_lshl_add_u32 v74, v53, 2, 0
	v_lshl_add_u32 v76, v54, 2, 0
	v_lshl_add_u32 v78, v55, 2, 0
	v_lshl_add_u32 v80, v56, 2, 0
	ds_read_b32 v52, v20
	ds_read_b32 v53, v21
	ds_read_b32 v54, v22
	ds_read_b32 v55, v23
	ds_read_b32 v56, v57
	ds_read_b32 v58, v24
	ds_read_b32 v59, v25
	ds_read_b32 v57, v18
	v_and_b32_e32 v60, 0xff8, v60
	v_and_b32_e32 v61, 0xff8, v61
	s_waitcnt lgkmcnt(14)
	v_pk_mul_f32 v[22:23], v[8:9], s[8:9] op_sel_hi:[1,0]
	v_pk_mul_f32 v[24:25], v[12:13], s[8:9] op_sel_hi:[1,0]
	s_waitcnt lgkmcnt(12)
	v_pk_mul_f32 v[20:21], v[14:15], s[8:9] op_sel_hi:[1,0]
	s_waitcnt lgkmcnt(10)
	v_pk_mul_f32 v[18:19], v[16:17], s[8:9] op_sel_hi:[1,0]
	v_and_b32_e32 v62, 0xff8, v62
	v_and_b32_e32 v63, 0xff8, v63
	v_and_b32_e32 v64, 0xff8, v64
	v_lshl_add_u32 v71, v60, 2, 0
	v_lshl_add_u32 v73, v61, 2, 0
	s_waitcnt lgkmcnt(3)
	v_mov_b32_e32 v61, v56
	v_pk_mul_f32 v[16:17], v[50:51], s[8:9] op_sel_hi:[1,0]
	v_pk_mul_f32 v[14:15], v[52:53], s[8:9] op_sel_hi:[1,0]
	v_pk_mul_f32 v[12:13], v[54:55], s[8:9] op_sel_hi:[1,0]
	s_waitcnt lgkmcnt(1)
	v_pk_mul_f32 v[8:9], v[58:59], s[8:9] op_sel_hi:[1,0]
	s_waitcnt lgkmcnt(0)
	v_pk_mul_f32 v[50:51], v[22:23], v[56:57]
	v_mov_b32_e32 v60, v57
	v_pk_mul_f32 v[52:53], v[24:25], v[56:57]
	v_pk_mul_f32 v[54:55], v[20:21], v[56:57]
	v_pk_mul_f32 v[58:59], v[18:19], v[56:57]
	v_lshl_add_u32 v68, v65, 2, 0
	v_lshl_add_u32 v70, v66, 2, 0
	v_lshl_add_u32 v75, v62, 2, 0
	v_lshl_add_u32 v77, v63, 2, 0
	v_lshl_add_u32 v79, v64, 2, 0
	v_pk_mul_f32 v[62:63], v[16:17], v[56:57]
	v_pk_mul_f32 v[64:65], v[14:15], v[56:57]
	v_pk_mul_f32 v[66:67], v[12:13], v[56:57]
	v_pk_mul_f32 v[56:57], v[8:9], v[56:57]
	v_sub_f32_e32 v81, v50, v51
	v_pk_mul_f32 v[50:51], v[22:23], v[60:61]
	v_sub_f32_e32 v82, v52, v53
	v_pk_mul_f32 v[52:53], v[24:25], v[60:61]
	v_sub_f32_e32 v83, v54, v55
	v_pk_mul_f32 v[54:55], v[20:21], v[60:61]
	v_sub_f32_e32 v84, v58, v59
	v_pk_mul_f32 v[58:59], v[18:19], v[60:61]
	v_sub_f32_e32 v85, v62, v63
	v_pk_mul_f32 v[62:63], v[16:17], v[60:61]
	v_sub_f32_e32 v86, v64, v65
	v_pk_mul_f32 v[64:65], v[14:15], v[60:61]
	v_sub_f32_e32 v87, v66, v67
	v_pk_mul_f32 v[66:67], v[12:13], v[60:61]
	v_sub_f32_e32 v88, v56, v57
	v_pk_mul_f32 v[56:57], v[60:61], v[8:9]
	v_add_f32_e32 v60, v51, v50
	v_add_f32_e32 v61, v53, v52
	v_add_f32_e32 v54, v55, v54
	v_add_f32_e32 v55, v59, v58
	v_cvt_pk_bf16_f32 v50, v81, v82
	v_cvt_pk_bf16_f32 v51, v83, v84
	v_cvt_pk_bf16_f32 v52, v85, v86
	v_cvt_pk_bf16_f32 v53, v87, v88
	v_add_f32_e32 v58, v63, v62
	v_add_f32_e32 v59, v65, v64
	v_add_f32_e32 v62, v67, v66
	v_add_f32_e32 v56, v57, v56
	global_store_dwordx4 v[2:3], v[50:53], off nt
	v_add_co_u32_e32 v6, vcc, s3, v2
	s_nop 0
	v_cvt_pk_bf16_f32 v50, v60, v61
	v_cvt_pk_bf16_f32 v51, v54, v55
	v_cvt_pk_bf16_f32 v52, v58, v59
	v_cvt_pk_bf16_f32 v53, v62, v56
	ds_read_b32 v54, v49
	ds_read_b32 v55, v68
	v_addc_co_u32_e32 v7, vcc, 0, v3, vcc
	v_add_co_u32_e32 v4, vcc, s17, v2
	s_waitcnt lgkmcnt(0)
; __device__ __forceinline__ unsigned cvt_pk_bf16(float lo, float hi) { unsigned r; asm volatile("v_cvt_pk_bf16_f32 %0, %1, %2" : "=v"(r) : "v"(lo), "v"(hi)); return r; }
; #define ST16(grp, p, v) do { if ((NTG >> (grp)) & 1) NT16(p, v); else PL16(p, v); } while (0)
; __device__ __forceinline__ void gen_dftl(unsigned char* ws, LAS unsigned char* lds, int first) {
;     ...
;         for (int i = 0; i < 8; ++i) { const int n0 = 8 * (lane + 64 * i), idx0 = (k * n0) & 4095; const float c0 = lut[idx0], s0 = lut[(idx0 - 1024) & 4095]; float vc[8], vs[8];
; #pragma unroll
;             for (int j = 0; j < 8; ++j) { vc[j] = c0 * cj[j] - s0 * sj[j]; vs[j] = s0 * cj[j] + c0 * sj[j]; }
;             u32x4 o; o.x = cvt_pk_bf16(vc[0], vc[1]); o.y = cvt_pk_bf16(vc[2], vc[3]); o.z = cvt_pk_bf16(vc[4], vc[5]); o.w = cvt_pk_bf16(vc[6], vc[7]);
;             ST16(6, DL + (size_t)k * 8192 + n0, o);
;             o.x = cvt_pk_bf16(vs[0], vs[1]); o.y = cvt_pk_bf16(vs[2], vs[3]); o.z = cvt_pk_bf16(vs[4], vs[5]); o.w = cvt_pk_bf16(vs[6], vs[7]);
;             ST16(6, DL + (size_t)k * 8192 + 4096 + n0, o); }
	v_pk_mul_f32 v[56:57], v[24:25], v[54:55]
	v_addc_co_u32_e32 v5, vcc, 0, v3, vcc
	global_store_dwordx4 v[4:5], v[50:53], off offset:-4096 nt
	v_pk_mul_f32 v[58:59], v[20:21], v[54:55]
	v_pk_mul_f32 v[60:61], v[18:19], v[54:55]
	v_pk_mul_f32 v[50:51], v[22:23], v[54:55]
	v_mov_b32_e32 v52, v55
	v_mov_b32_e32 v53, v54
	v_pk_mul_f32 v[62:63], v[16:17], v[54:55]
	v_pk_mul_f32 v[64:65], v[14:15], v[54:55]
	v_pk_mul_f32 v[66:67], v[12:13], v[54:55]
	v_pk_mul_f32 v[54:55], v[8:9], v[54:55]
	v_sub_f32_e32 v49, v50, v51
	v_pk_mul_f32 v[50:51], v[22:23], v[52:53]
	v_sub_f32_e32 v68, v56, v57
	v_pk_mul_f32 v[56:57], v[24:25], v[52:53]
	v_sub_f32_e32 v81, v58, v59
	v_pk_mul_f32 v[58:59], v[20:21], v[52:53]
	v_sub_f32_e32 v82, v60, v61
	v_pk_mul_f32 v[60:61], v[18:19], v[52:53]
	v_sub_f32_e32 v83, v62, v63
	v_pk_mul_f32 v[62:63], v[16:17], v[52:53]
	v_sub_f32_e32 v84, v64, v65
	v_pk_mul_f32 v[64:65], v[14:15], v[52:53]
	v_sub_f32_e32 v85, v66, v67
	v_pk_mul_f32 v[66:67], v[12:13], v[52:53]
	v_pk_mul_f32 v[52:53], v[8:9], v[52:53]
	v_sub_f32_e32 v54, v54, v55
	v_add_f32_e32 v55, v51, v50
	v_add_f32_e32 v56, v57, v56
	v_add_f32_e32 v57, v59, v58
	v_add_f32_e32 v59, v63, v62
	v_add_f32_e32 v62, v53, v52
	v_cvt_pk_bf16_f32 v50, v49, v68
	v_cvt_pk_bf16_f32 v51, v81, v82
	v_cvt_pk_bf16_f32 v52, v83, v84
	v_cvt_pk_bf16_f32 v53, v85, v54
	v_add_f32_e32 v58, v61, v60
	v_add_f32_e32 v60, v65, v64
	v_add_f32_e32 v61, v67, v66
	global_store_dwordx4 v[2:3], v[50:53], off offset:1024 nt
	v_add_co_u32_e32 v10, vcc, s18, v2
	s_nop 0
	v_cvt_pk_bf16_f32 v50, v55, v56
	v_cvt_pk_bf16_f32 v51, v57, v58
	v_cvt_pk_bf16_f32 v52, v59, v60
	v_cvt_pk_bf16_f32 v53, v61, v62
	ds_read_b32 v54, v69
	ds_read_b32 v55, v70
	global_store_dwordx4 v[6:7], v[50:53], off offset:1024 nt
	v_addc_co_u32_e32 v11, vcc, 0, v3, vcc
	s_waitcnt lgkmcnt(1)
	v_mov_b32_e32 v53, v54
	s_waitcnt lgkmcnt(0)
	v_pk_mul_f32 v[50:51], v[22:23], v[54:55]
	v_mov_b32_e32 v52, v55
	v_pk_mul_f32 v[56:57], v[24:25], v[54:55]
	v_pk_mul_f32 v[58:59], v[20:21], v[54:55]
	v_pk_mul_f32 v[60:61], v[18:19], v[54:55]
	v_pk_mul_f32 v[62:63], v[16:17], v[54:55]
	v_pk_mul_f32 v[64:65], v[14:15], v[54:55]
	v_pk_mul_f32 v[66:67], v[12:13], v[54:55]
	v_pk_mul_f32 v[54:55], v[8:9], v[54:55]
	v_sub_f32_e32 v49, v50, v51
	v_pk_mul_f32 v[50:51], v[22:23], v[52:53]
	v_sub_f32_e32 v68, v56, v57
	v_pk_mul_f32 v[56:57], v[24:25], v[52:53]
	v_sub_f32_e32 v69, v58, v59
	v_pk_mul_f32 v[58:59], v[20:21], v[52:53]
	v_sub_f32_e32 v70, v60, v61
	v_pk_mul_f32 v[60:61], v[18:19], v[52:53]
	v_sub_f32_e32 v81, v62, v63
	v_pk_mul_f32 v[62:63], v[16:17], v[52:53]
	v_sub_f32_e32 v82, v64, v65
	v_pk_mul_f32 v[64:65], v[14:15], v[52:53]
	v_sub_f32_e32 v83, v66, v67
	v_pk_mul_f32 v[66:67], v[12:13], v[52:53]
	v_pk_mul_f32 v[52:53], v[8:9], v[52:53]
	v_sub_f32_e32 v54, v54, v55
	v_add_f32_e32 v55, v51, v50
	v_add_f32_e32 v56, v57, v56
	v_add_f32_e32 v57, v59, v58
	v_add_f32_e32 v59, v63, v62
	v_add_f32_e32 v62, v53, v52
	v_cvt_pk_bf16_f32 v50, v49, v68
	v_cvt_pk_bf16_f32 v51, v69, v70
	v_cvt_pk_bf16_f32 v52, v81, v82
	v_cvt_pk_bf16_f32 v53, v83, v54
	v_add_f32_e32 v58, v61, v60
	v_add_f32_e32 v60, v65, v64
	v_add_f32_e32 v61, v67, v66
	global_store_dwordx4 v[2:3], v[50:53], off offset:2048 nt
	v_add_u32_e32 v0, s2, v0
	v_cmp_lt_i32_e32 vcc, s19, v0
	v_cvt_pk_bf16_f32 v50, v55, v56
	v_cvt_pk_bf16_f32 v51, v57, v58
	v_cvt_pk_bf16_f32 v52, v59, v60
	v_cvt_pk_bf16_f32 v53, v61, v62
	ds_read_b32 v54, v71
	ds_read_b32 v55, v72
	global_store_dwordx4 v[6:7], v[50:53], off offset:2048 nt
	v_add_u32_e32 v26, s9, v26
	v_add_u32_e32 v27, s10, v27
	s_waitcnt lgkmcnt(1)
	v_mov_b32_e32 v53, v54
	s_waitcnt lgkmcnt(0)
	v_pk_mul_f32 v[50:51], v[22:23], v[54:55]
	v_mov_b32_e32 v52, v55
	v_pk_mul_f32 v[56:57], v[24:25], v[54:55]
	v_pk_mul_f32 v[58:59], v[20:21], v[54:55]
	v_pk_mul_f32 v[60:61], v[18:19], v[54:55]
	v_pk_mul_f32 v[62:63], v[16:17], v[54:55]
	v_pk_mul_f32 v[64:65], v[14:15], v[54:55]
	v_pk_mul_f32 v[66:67], v[12:13], v[54:55]
	v_pk_mul_f32 v[54:55], v[8:9], v[54:55]
	v_sub_f32_e32 v49, v50, v51
	v_pk_mul_f32 v[50:51], v[22:23], v[52:53]
	v_sub_f32_e32 v68, v56, v57
	v_pk_mul_f32 v[56:57], v[24:25], v[52:53]
	v_sub_f32_e32 v69, v58, v59
	v_pk_mul_f32 v[58:59], v[20:21], v[52:53]
	v_sub_f32_e32 v70, v60, v61
	v_pk_mul_f32 v[60:61], v[18:19], v[52:53]
	v_sub_f32_e32 v71, v62, v63
	v_pk_mul_f32 v[62:63], v[16:17], v[52:53]
	v_sub_f32_e32 v72, v64, v65
	v_pk_mul_f32 v[64:65], v[14:15], v[52:53]
	v_sub_f32_e32 v81, v66, v67
	v_pk_mul_f32 v[66:67], v[12:13], v[52:53]
	v_pk_mul_f32 v[52:53], v[8:9], v[52:53]
	v_sub_f32_e32 v54, v54, v55
	v_add_f32_e32 v55, v51, v50
	v_add_f32_e32 v56, v57, v56
	v_add_f32_e32 v57, v59, v58
	v_add_f32_e32 v59, v63, v62
	v_add_f32_e32 v62, v53, v52
	v_cvt_pk_bf16_f32 v50, v49, v68
	v_cvt_pk_bf16_f32 v51, v69, v70
	v_cvt_pk_bf16_f32 v52, v71, v72
	v_cvt_pk_bf16_f32 v53, v81, v54
	v_add_f32_e32 v58, v61, v60
	v_add_f32_e32 v60, v65, v64
	v_add_f32_e32 v61, v67, v66
	global_store_dwordx4 v[2:3], v[50:53], off offset:3072 nt
	v_add_u32_e32 v28, s11, v28
	v_add_u32_e32 v29, s12, v29
	v_cvt_pk_bf16_f32 v50, v55, v56
	v_cvt_pk_bf16_f32 v51, v57, v58
	v_cvt_pk_bf16_f32 v52, v59, v60
	v_cvt_pk_bf16_f32 v53, v61, v62
	ds_read_b32 v54, v73
	ds_read_b32 v55, v74
	global_store_dwordx4 v[6:7], v[50:53], off offset:3072 nt
	v_add_u32_e32 v30, s13, v30
	v_add_u32_e32 v31, s16, v31
	s_waitcnt lgkmcnt(1)
	v_mov_b32_e32 v51, v54
	s_waitcnt lgkmcnt(0)
; __device__ __forceinline__ unsigned cvt_pk_bf16(float lo, float hi) { unsigned r; asm volatile("v_cvt_pk_bf16_f32 %0, %1, %2" : "=v"(r) : "v"(lo), "v"(hi)); return r; }
; #define ST16(grp, p, v) do { if ((NTG >> (grp)) & 1) NT16(p, v); else PL16(p, v); } while (0)
; __device__ __forceinline__ void gen_dftl(unsigned char* ws, LAS unsigned char* lds, int first) {
;     ...
;         for (int i = 0; i < 8; ++i) { const int n0 = 8 * (lane + 64 * i), idx0 = (k * n0) & 4095; const float c0 = lut[idx0], s0 = lut[(idx0 - 1024) & 4095]; float vc[8], vs[8];
; #pragma unroll
;             for (int j = 0; j < 8; ++j) { vc[j] = c0 * cj[j] - s0 * sj[j]; vs[j] = s0 * cj[j] + c0 * sj[j]; }
;             u32x4 o; o.x = cvt_pk_bf16(vc[0], vc[1]); o.y = cvt_pk_bf16(vc[2], vc[3]); o.z = cvt_pk_bf16(vc[4], vc[5]); o.w = cvt_pk_bf16(vc[6], vc[7]);
;             ST16(6, DL + (size_t)k * 8192 + n0, o);
;             o.x = cvt_pk_bf16(vs[0], vs[1]); o.y = cvt_pk_bf16(vs[2], vs[3]); o.z = cvt_pk_bf16(vs[4], vs[5]); o.w = cvt_pk_bf16(vs[6], vs[7]);
;             ST16(6, DL + (size_t)k * 8192 + 4096 + n0, o); }
	v_pk_mul_f32 v[6:7], v[22:23], v[54:55]
	v_mov_b32_e32 v50, v55
	v_pk_mul_f32 v[52:53], v[24:25], v[54:55]
	v_pk_mul_f32 v[56:57], v[20:21], v[54:55]
	v_pk_mul_f32 v[58:59], v[18:19], v[54:55]
	v_pk_mul_f32 v[60:61], v[16:17], v[54:55]
	v_pk_mul_f32 v[62:63], v[14:15], v[54:55]
	v_pk_mul_f32 v[64:65], v[12:13], v[54:55]
	v_pk_mul_f32 v[54:55], v[8:9], v[54:55]
	v_sub_f32_e32 v49, v6, v7
	v_pk_mul_f32 v[6:7], v[22:23], v[50:51]
	v_sub_f32_e32 v66, v52, v53
	v_pk_mul_f32 v[52:53], v[24:25], v[50:51]
	v_sub_f32_e32 v67, v56, v57
	v_pk_mul_f32 v[56:57], v[20:21], v[50:51]
	v_sub_f32_e32 v68, v58, v59
	v_pk_mul_f32 v[58:59], v[18:19], v[50:51]
	v_sub_f32_e32 v69, v60, v61
	v_pk_mul_f32 v[60:61], v[16:17], v[50:51]
	v_sub_f32_e32 v70, v62, v63
	v_pk_mul_f32 v[62:63], v[14:15], v[50:51]
	v_sub_f32_e32 v71, v64, v65
	v_pk_mul_f32 v[64:65], v[12:13], v[50:51]
	v_pk_mul_f32 v[50:51], v[8:9], v[50:51]
	v_sub_f32_e32 v54, v54, v55
	v_add_f32_e32 v6, v7, v6
	v_add_f32_e32 v7, v53, v52
	v_add_f32_e32 v55, v57, v56
	v_add_f32_e32 v57, v61, v60
	v_add_f32_e32 v60, v51, v50
	v_cvt_pk_bf16_f32 v50, v49, v66
	v_cvt_pk_bf16_f32 v51, v67, v68
	v_cvt_pk_bf16_f32 v52, v69, v70
	v_cvt_pk_bf16_f32 v53, v71, v54
	v_add_f32_e32 v56, v59, v58
	v_add_f32_e32 v58, v63, v62
	v_add_f32_e32 v59, v65, v64
	global_store_dwordx4 v[10:11], v[50:53], off nt
	v_add_u32_e32 v33, v33, v35
	v_add_u32_e32 v36, v36, v37
	v_cvt_pk_bf16_f32 v50, v6, v7
	v_cvt_pk_bf16_f32 v51, v55, v56
	v_cvt_pk_bf16_f32 v52, v57, v58
	v_cvt_pk_bf16_f32 v53, v59, v60
	ds_read_b32 v6, v75
	ds_read_b32 v7, v76
	global_store_dwordx4 v[4:5], v[50:53], off nt
	v_add_u32_e32 v38, v38, v39
	v_add_u32_e32 v40, v40, v41
	s_waitcnt lgkmcnt(1)
	v_mov_b32_e32 v53, v6
	s_waitcnt lgkmcnt(0)
	v_pk_mul_f32 v[50:51], v[22:23], v[6:7]
	v_mov_b32_e32 v52, v7
	v_pk_mul_f32 v[54:55], v[24:25], v[6:7]
	v_pk_mul_f32 v[56:57], v[20:21], v[6:7]
	v_pk_mul_f32 v[58:59], v[18:19], v[6:7]
	v_pk_mul_f32 v[60:61], v[16:17], v[6:7]
	v_pk_mul_f32 v[62:63], v[14:15], v[6:7]
	v_pk_mul_f32 v[64:65], v[12:13], v[6:7]
	v_pk_mul_f32 v[6:7], v[8:9], v[6:7]
	v_sub_f32_e32 v49, v50, v51
	v_pk_mul_f32 v[50:51], v[22:23], v[52:53]
	v_sub_f32_e32 v72, v6, v7
	v_pk_mul_f32 v[6:7], v[8:9], v[52:53]
	v_sub_f32_e32 v66, v54, v55
	v_pk_mul_f32 v[54:55], v[24:25], v[52:53]
	v_sub_f32_e32 v67, v56, v57
	v_pk_mul_f32 v[56:57], v[20:21], v[52:53]
	v_sub_f32_e32 v68, v58, v59
	v_pk_mul_f32 v[58:59], v[18:19], v[52:53]
	v_sub_f32_e32 v69, v60, v61
	v_pk_mul_f32 v[60:61], v[16:17], v[52:53]
	v_sub_f32_e32 v70, v62, v63
	v_pk_mul_f32 v[62:63], v[14:15], v[52:53]
	v_sub_f32_e32 v71, v64, v65
	v_pk_mul_f32 v[64:65], v[12:13], v[52:53]
	v_add_f32_e32 v73, v51, v50
	v_add_f32_e32 v6, v7, v6
	v_cvt_pk_bf16_f32 v50, v49, v66
	v_cvt_pk_bf16_f32 v51, v67, v68
	v_cvt_pk_bf16_f32 v52, v69, v70
	v_cvt_pk_bf16_f32 v53, v71, v72
	v_add_f32_e32 v54, v55, v54
	v_add_f32_e32 v55, v57, v56
	v_add_f32_e32 v56, v59, v58
	v_add_f32_e32 v57, v61, v60
	v_add_f32_e32 v58, v63, v62
	v_add_f32_e32 v59, v65, v64
	global_store_dwordx4 v[10:11], v[50:53], off offset:1024 nt
	v_add_u32_e32 v42, v42, v43
	v_add_u32_e32 v44, v44, v45
	v_cvt_pk_bf16_f32 v50, v73, v54
	v_cvt_pk_bf16_f32 v51, v55, v56
	v_cvt_pk_bf16_f32 v52, v57, v58
	v_cvt_pk_bf16_f32 v53, v59, v6
	ds_read_b32 v6, v77
	ds_read_b32 v7, v78
	global_store_dwordx4 v[4:5], v[50:53], off offset:1024 nt
	v_add_u32_e32 v46, v46, v47
	v_add_u32_e32 v1, v1, v34
	s_waitcnt lgkmcnt(1)
	v_mov_b32_e32 v53, v6
	s_waitcnt lgkmcnt(0)
	v_pk_mul_f32 v[50:51], v[22:23], v[6:7]
	v_mov_b32_e32 v52, v7
	v_pk_mul_f32 v[54:55], v[24:25], v[6:7]
	v_pk_mul_f32 v[56:57], v[20:21], v[6:7]
	v_pk_mul_f32 v[58:59], v[18:19], v[6:7]
	v_pk_mul_f32 v[60:61], v[16:17], v[6:7]
	v_pk_mul_f32 v[62:63], v[14:15], v[6:7]
	v_pk_mul_f32 v[64:65], v[12:13], v[6:7]
	v_pk_mul_f32 v[6:7], v[8:9], v[6:7]
	v_sub_f32_e32 v49, v50, v51
	v_pk_mul_f32 v[50:51], v[22:23], v[52:53]
	v_sub_f32_e32 v72, v6, v7
	v_pk_mul_f32 v[6:7], v[8:9], v[52:53]
	v_sub_f32_e32 v66, v54, v55
	v_pk_mul_f32 v[54:55], v[24:25], v[52:53]
	v_sub_f32_e32 v67, v56, v57
	v_pk_mul_f32 v[56:57], v[20:21], v[52:53]
	v_sub_f32_e32 v68, v58, v59
	v_pk_mul_f32 v[58:59], v[18:19], v[52:53]
	v_sub_f32_e32 v69, v60, v61
	v_pk_mul_f32 v[60:61], v[16:17], v[52:53]
	v_sub_f32_e32 v70, v62, v63
	v_pk_mul_f32 v[62:63], v[14:15], v[52:53]
	v_sub_f32_e32 v71, v64, v65
	v_pk_mul_f32 v[64:65], v[12:13], v[52:53]
	v_add_f32_e32 v73, v51, v50
	v_add_f32_e32 v6, v7, v6
	v_cvt_pk_bf16_f32 v50, v49, v66
	v_cvt_pk_bf16_f32 v51, v67, v68
	v_cvt_pk_bf16_f32 v52, v69, v70
	v_cvt_pk_bf16_f32 v53, v71, v72
	v_add_f32_e32 v54, v55, v54
	v_add_f32_e32 v55, v57, v56
	v_add_f32_e32 v56, v59, v58
	v_add_f32_e32 v57, v61, v60
	v_add_f32_e32 v58, v63, v62
	v_add_f32_e32 v59, v65, v64
	global_store_dwordx4 v[10:11], v[50:53], off offset:2048 nt
	s_or_b64 s[6:7], vcc, s[6:7]
	v_lshl_add_u64 v[2:3], v[2:3], 0, s[4:5]
	v_cvt_pk_bf16_f32 v50, v73, v54
	v_cvt_pk_bf16_f32 v51, v55, v56
	v_cvt_pk_bf16_f32 v52, v57, v58
	v_cvt_pk_bf16_f32 v53, v59, v6
	ds_read_b32 v6, v79
	ds_read_b32 v7, v80
	global_store_dwordx4 v[4:5], v[50:53], off offset:2048 nt
	s_waitcnt lgkmcnt(0)
	v_pk_mul_f32 v[54:55], v[24:25], v[6:7]
	v_pk_mul_f32 v[50:51], v[22:23], v[6:7]
	v_mov_b32_e32 v52, v7
	v_mov_b32_e32 v53, v6
	v_pk_mul_f32 v[56:57], v[20:21], v[6:7]
	v_pk_mul_f32 v[58:59], v[18:19], v[6:7]
	v_pk_mul_f32 v[60:61], v[16:17], v[6:7]
	v_pk_mul_f32 v[62:63], v[14:15], v[6:7]
	v_pk_mul_f32 v[64:65], v[12:13], v[6:7]
	v_pk_mul_f32 v[6:7], v[8:9], v[6:7]
	v_sub_f32_e32 v49, v50, v51
	v_sub_f32_e32 v50, v54, v55
	v_sub_f32_e32 v54, v58, v59
	v_pk_mul_f32 v[12:13], v[12:13], v[52:53]
	v_sub_f32_e32 v58, v6, v7
	v_pk_mul_f32 v[6:7], v[8:9], v[52:53]
	v_pk_mul_f32 v[22:23], v[22:23], v[52:53]
	v_pk_mul_f32 v[24:25], v[24:25], v[52:53]
	v_sub_f32_e32 v51, v56, v57
	v_pk_mul_f32 v[20:21], v[20:21], v[52:53]
	v_pk_mul_f32 v[18:19], v[18:19], v[52:53]
	v_sub_f32_e32 v55, v60, v61
	v_pk_mul_f32 v[16:17], v[16:17], v[52:53]
	v_sub_f32_e32 v56, v62, v63
	v_pk_mul_f32 v[14:15], v[14:15], v[52:53]
	v_sub_f32_e32 v57, v64, v65
	v_add_f32_e32 v12, v13, v12
	v_add_f32_e32 v13, v7, v6
	v_cvt_pk_bf16_f32 v6, v49, v50
	v_cvt_pk_bf16_f32 v7, v51, v54
	v_cvt_pk_bf16_f32 v8, v55, v56
	v_cvt_pk_bf16_f32 v9, v57, v58
	v_add_f32_e32 v22, v23, v22
	v_add_f32_e32 v23, v25, v24
	v_add_f32_e32 v20, v21, v20
	v_add_f32_e32 v18, v19, v18
	v_add_f32_e32 v16, v17, v16
	v_add_f32_e32 v14, v15, v14
	global_store_dwordx4 v[10:11], v[6:9], off offset:3072 nt
	s_nop 1
	v_cvt_pk_bf16_f32 v6, v22, v23
	v_cvt_pk_bf16_f32 v7, v20, v18
	v_cvt_pk_bf16_f32 v8, v16, v14
	v_cvt_pk_bf16_f32 v9, v12, v13
	global_store_dwordx4 v[4:5], v[6:9], off offset:3072 nt
	s_andn2_b64 exec, exec, s[6:7]
	s_cbranch_execnz .LBB0_424
